# fused w_out tile ownership changed from 4 row x 8 column tiles per XCD to 8 x 4 (the row-sum exchange then spans an XCD pair)
# speedup vs baseline: 1.0048x; 1.0048x over previous
.LBB0_1166:
	s_mov_b32 s2, s44
	s_mov_b32 s3, 0
	s_mov_b32 s94, 0
	s_mov_b32 s95, 28
	s_cmpk_eq_u32 s16, 0x40
	s_cbranch_scc0 .Lgo_fz_no
	v_readlane_b32 s0, v254, 1
	s_cmpk_eq_u32 s0, 0x100
	s_cbranch_scc0 .Lgo_fz_no
	s_mov_b32 s3, 3
	s_and_b32 s0, s44, 7
	s_lshr_b32 s1, s44, 3
	s_lshr_b32 s2, s1, 5
	s_and_b32 s1, s1, 31
	s_lshl_b32 s2, s2, 5
	s_and_b32 vcc_lo, s0, 3
	s_lshl_b32 vcc_lo, vcc_lo, 3
	s_add_u32 s2, s2, vcc_lo
	s_and_b32 vcc_lo, s1, 7
	s_add_u32 s2, s2, vcc_lo
	s_lshr_b32 s1, s1, 3
	s_lshr_b32 s0, s0, 2
	s_lshl_b32 s0, s0, 2
	s_add_u32 s1, s1, s0
	s_lshl_b32 s1, s1, 3
	s_and_b32 s0, s2, 7
	s_or_b32 s1, s1, s0
	s_lshr_b32 s0, s2, 3
	s_lshl_b32 s1, s1, 3
	s_or_b32 s2, s1, s0
	s_branch .Lgo_sk_dec

.Lgo_sk_dec:
	s_cmpk_eq_u32 s16, 0x44
	s_cbranch_scc0 .Lgo_fz_dec
	v_readlane_b32 s0, v254, 1
	s_cmpk_eq_u32 s0, 0x100
	s_cbranch_scc0 .Lgo_fz_dec
	s_mov_b32 s0, s2
	s_cmpk_lt_u32 s2, 0x200
	s_cbranch_scc0 .Lgo_fz_w68
	s_mov_b32 s3, 3
	s_and_b32 s0, s2, 7
	s_lshr_b32 s1, s2, 3
	s_lshr_b32 s34, s1, 5
	s_and_b32 s1, s1, 31
	s_lshl_b32 s34, s34, 5
	s_and_b32 vcc_lo, s0, 3
	s_lshl_b32 vcc_lo, vcc_lo, 3
	s_add_u32 s34, s34, vcc_lo
	s_and_b32 vcc_lo, s1, 7
	s_add_u32 s34, s34, vcc_lo
	s_lshr_b32 s1, s1, 3
	s_lshr_b32 s0, s0, 2
	s_lshl_b32 s0, s0, 2
	s_add_u32 s1, s1, s0
	s_lshl_b32 s1, s1, 3
	s_and_b32 s0, s34, 7
	s_or_b32 s1, s1, s0
	s_lshr_b32 s0, s34, 3
	s_lshl_b32 s0, s0, 6
	s_or_b32 s0, s0, s1
